# attention items: next key chunk staged into the other LDS buffer under the softmax (operands fetched two chunks ahead, stores off the barrier path); epilogue gate/g_att operands prefetched in the item
# baseline (speedup 1.0000x reference)
.LBB0_1100:
	s_load_dwordx2 s[4:5], s[82:83], 0x40
	v_lshlrev_b32_e32 v0, 1, v208
	v_mov_b32_e32 v1, v209
	v_or_b32_e32 v12, s8, v208
	v_ashrrev_i32_e32 v13, 31, v12
	s_waitcnt lgkmcnt(0)
	s_add_u32 s76, s4, s14
	s_addc_u32 s77, s5, s15
	s_add_i32 s4, s8, 0x1000
	s_ashr_i32 s4, s4, 7
	s_ashr_i32 s5, s4, 31
	s_lshl_b64 s[4:5], s[4:5], 21
	s_add_u32 s4, s80, s4
	s_addc_u32 s5, s81, s5
	v_lshl_add_u64 v[2:3], s[4:5], 0, v[98:99]
	v_lshl_add_u64 v[10:11], v[2:3], 0, v[0:1]
	v_mov_b64_e32 v[14:15], v[202:203]
	v_mov_b32_e32 v2, v135
	s_nop 1
	v_permlane16_swap_b32_e32 v135, v2
	v_lshlrev_b64 v[0:1], 12, v[96:97]
	v_lshl_add_u64 v[0:1], s[56:57], 0, v[0:1]
	v_lshl_add_u64 v[4:5], v[0:1], 0, s[68:69]
	v_lshl_add_u64 v[0:1], v[12:13], 2, s[76:77]
	s_waitcnt lgkmcnt(0)
	v_add_f32_e32 v2, v135, v2
	v_mov_b32_e32 v3, v2
	s_nop 1
	v_permlane32_swap_b32_e32 v2, v3
	s_ashr_i32 s9, s8, 31
	s_mov_b32 s86, s46
	s_waitcnt lgkmcnt(0)
	v_add_f32_e32 v6, v2, v3
	v_div_scale_f32 v7, s[4:5], v6, v6, 1.0
	v_rcp_f32_e32 v8, v7
	v_div_scale_f32 v9, vcc, 1.0, v6, 1.0
	v_mov_b64_e32 v[0:1], v[204:205]
	v_mov_b64_e32 v[2:3], v[206:207]
	s_waitcnt vmcnt(8)
	v_fma_f32 v32, -v7, v8, 1.0
	v_fmac_f32_e32 v8, v32, v8
	v_mul_f32_e32 v32, v9, v8
	v_fma_f32 v33, -v7, v32, v9
	v_fmac_f32_e32 v32, v33, v8
	v_fma_f32 v7, -v7, v32, v9
	v_div_fmas_f32 v7, v7, v8, v32
	s_waitcnt vmcnt(6)
	v_div_fixup_f32 v46, v7, v6, 1.0
	v_pk_mul_f32 v[6:7], v[76:77], v[46:47] op_sel_hi:[1,0]
	v_pk_mul_f32 v[8:9], v[78:79], v[46:47] op_sel_hi:[1,0]
	v_pk_mul_f32 v[40:41], v[74:75], v[46:47] op_sel_hi:[1,0]
	v_pk_mul_f32 v[42:43], v[72:73], v[46:47] op_sel_hi:[1,0]
	v_pk_mul_f32 v[44:45], v[70:71], v[46:47] op_sel_hi:[1,0]
	s_waitcnt vmcnt(5)
	v_pk_mul_f32 v[48:49], v[68:69], v[46:47] op_sel_hi:[1,0]
	v_pk_mul_f32 v[34:35], v[58:59], v[46:47] op_sel_hi:[1,0]
	v_pk_mul_f32 v[38:39], v[56:57], v[46:47] op_sel_hi:[1,0]
	v_pk_mul_f32 v[32:33], v[18:19], v[46:47] op_sel_hi:[1,0]
	v_pk_mul_f32 v[56:57], v[42:43], v[42:43]
	s_waitcnt vmcnt(4)
	v_pk_mul_f32 v[54:55], v[40:41], v[40:41]
	s_waitcnt vmcnt(3)
	v_pk_mul_f32 v[60:61], v[48:49], v[48:49]
	v_pk_mul_f32 v[58:59], v[44:45], v[44:45]
	s_waitcnt vmcnt(2)
	v_pk_mul_f32 v[64:65], v[38:39], v[38:39]
	v_pk_mul_f32 v[62:63], v[34:35], v[34:35]
	v_pk_mul_f32 v[66:67], v[32:33], v[32:33]
	v_pk_mul_f32 v[50:51], v[6:7], v[6:7]
	v_pk_mul_f32 v[52:53], v[8:9], v[8:9]
	s_waitcnt vmcnt(1)
	v_lshlrev_b32_e32 v37, 16, v14
	v_and_b32_e32 v47, 0xffff0000, v14
	v_lshlrev_b32_e32 v80, 16, v15
	v_and_b32_e32 v36, 0xffff0000, v15
	v_mul_f32_e32 v14, 0xbfb8aa3b, v37
	v_mul_f32_e32 v15, 0xbfb8aa3b, v47
	v_mul_f32_e32 v18, 0xbfb8aa3b, v80
	v_mul_f32_e32 v19, 0xbfb8aa3b, v36
	v_exp_f32_e32 v14, v14
	v_exp_f32_e32 v15, v15
	v_exp_f32_e32 v18, v18
	v_exp_f32_e32 v19, v19
	v_pk_add_f32 v[14:15], v[14:15], 1.0 op_sel_hi:[1,0]
	s_nop 0
	v_div_scale_f32 v70, s[4:5], v14, v14, v37
	v_pk_add_f32 v[68:69], v[18:19], 1.0 op_sel_hi:[1,0]
	v_div_scale_f32 v18, s[4:5], v15, v15, v47
	v_rcp_f32_e32 v74, v18
	v_div_scale_f32 v72, s[6:7], v69, v69, v36
	v_rcp_f32_e32 v75, v70
	v_rcp_f32_e32 v76, v72
	v_fma_f32 v77, -v18, v74, 1.0
	v_div_scale_f32 v19, vcc, v47, v15, v47
	v_fma_f32 v78, -v70, v75, 1.0
	v_fmac_f32_e32 v74, v77, v74
	v_div_scale_f32 v71, s[4:5], v37, v14, v37
	v_fma_f32 v79, -v72, v76, 1.0
	v_fmac_f32_e32 v75, v78, v75
	v_mul_f32_e32 v77, v19, v74
	v_div_scale_f32 v73, s[6:7], v36, v69, v36
	v_fmac_f32_e32 v76, v79, v76
	v_mul_f32_e32 v78, v71, v75
	v_fma_f32 v83, -v18, v77, v19
	v_mul_f32_e32 v79, v73, v76
	v_fma_f32 v84, -v70, v78, v71
	v_fmac_f32_e32 v77, v83, v74
	v_fma_f32 v85, -v72, v79, v73
	v_fmac_f32_e32 v78, v84, v75
	v_fma_f32 v18, -v18, v77, v19
	v_fmac_f32_e32 v79, v85, v76
	v_fma_f32 v19, -v70, v78, v71
	v_div_fmas_f32 v18, v18, v74, v77
	s_mov_b64 vcc, s[4:5]
	v_fma_f32 v72, -v72, v79, v73
	v_div_fixup_f32 v71, v18, v15, v47
	v_div_fmas_f32 v15, v19, v75, v78
	s_mov_b64 vcc, s[6:7]
	v_div_fixup_f32 v70, v15, v14, v37
	v_div_fmas_f32 v14, v72, v76, v79
	v_div_fixup_f32 v47, v14, v69, v36
	v_pk_mul_f32 v[36:37], v[16:17], v[46:47] op_sel_hi:[1,0]
	v_pk_mul_f32 v[30:31], v[30:31], v[46:47] op_sel_hi:[1,0]
	v_pk_mul_f32 v[28:29], v[28:29], v[46:47] op_sel_hi:[1,0]
	v_pk_mul_f32 v[22:23], v[22:23], v[46:47] op_sel_hi:[1,0]
	v_pk_mul_f32 v[20:21], v[20:21], v[46:47] op_sel_hi:[1,0]
	v_pk_mul_f32 v[16:17], v[26:27], v[46:47] op_sel_hi:[1,0]
	v_pk_mul_f32 v[18:19], v[24:25], v[46:47] op_sel_hi:[1,0]
	v_add_f32_e32 v46, v56, v57
	v_add_f32_e32 v46, v54, v46
	v_add_f32_e32 v46, v55, v46
	v_add_f32_e32 v46, v60, v46
	v_add_f32_e32 v46, v61, v46
	v_add_f32_e32 v46, v58, v46
	v_add_f32_e32 v46, v59, v46
	v_add_f32_e32 v46, v64, v46
	v_add_f32_e32 v46, v65, v46
	v_add_f32_e32 v46, v62, v46
	v_pk_mul_f32 v[14:15], v[36:37], v[36:37]
	v_add_f32_e32 v46, v63, v46
	v_add_f32_e32 v14, v14, v46
	v_add_f32_e32 v14, v15, v14
	v_add_f32_e32 v14, v66, v14
	v_pk_mul_f32 v[74:75], v[28:29], v[28:29]
	v_add_f32_e32 v14, v67, v14
	v_add_f32_e32 v14, v74, v14
	v_pk_mul_f32 v[72:73], v[30:31], v[30:31]
	v_add_f32_e32 v14, v75, v14
	v_add_f32_e32 v14, v72, v14
	v_pk_mul_f32 v[78:79], v[20:21], v[20:21]
	v_add_f32_e32 v14, v73, v14
	v_add_f32_e32 v14, v78, v14
	v_pk_mul_f32 v[76:77], v[22:23], v[22:23]
	v_add_f32_e32 v14, v79, v14
	v_add_f32_e32 v14, v76, v14
	v_pk_mul_f32 v[24:25], v[18:19], v[18:19]
	v_add_f32_e32 v14, v77, v14
	v_add_f32_e32 v14, v24, v14
	v_pk_mul_f32 v[26:27], v[16:17], v[16:17]
	v_add_f32_e32 v14, v25, v14
	v_add_f32_e32 v14, v26, v14
	v_add_f32_e32 v14, v27, v14
	v_add_f32_e32 v14, v50, v14
	v_add_f32_e32 v14, v51, v14
	v_add_f32_e32 v14, v52, v14
	v_add_f32_e32 v14, v53, v14
	v_mov_b32_e32 v15, v14
	s_nop 1
	v_permlane16_swap_b32_e32 v14, v15
	v_div_scale_f32 v81, s[22:23], v68, v68, v80
	v_rcp_f32_e32 v82, v81
	s_waitcnt lgkmcnt(0)
	v_add_f32_e32 v14, v14, v15
	v_mov_b32_e32 v15, v14
	s_nop 1
	v_permlane32_swap_b32_e32 v14, v15
	v_fma_f32 v24, -v81, v82, 1.0
	v_fmac_f32_e32 v82, v24, v82
	v_div_scale_f32 v24, vcc, v80, v68, v80
	s_waitcnt lgkmcnt(0)
	v_add_f32_e32 v14, v14, v15
	v_fmamk_f32 v14, v14, 0x3c000000, v231
	v_mul_f32_e32 v15, 0x4b800000, v14
	v_cmp_gt_f32_e64 s[4:5], s37, v14
	v_mul_f32_e32 v25, v24, v82
	v_fma_f32 v26, -v81, v25, v24
	v_cndmask_b32_e64 v14, v14, v15, s[4:5]
	v_rsq_f32_e32 v14, v14
	v_fmac_f32_e32 v25, v26, v82
	v_fma_f32 v24, -v81, v25, v24
	v_div_fmas_f32 v15, v24, v82, v25
	v_lshl_add_u64 v[24:25], v[12:13], 1, v[4:5]
	v_mul_f32_e32 v13, 0x45800000, v14
	v_cndmask_b32_e64 v14, v14, v13, s[4:5]
	v_pk_mul_f32 v[26:27], v[42:43], v[14:15] op_sel_hi:[1,0]
	v_div_fixup_f32 v46, v15, v68, v80
	s_waitcnt vmcnt(0)
	v_pk_mul_f32 v[0:1], v[0:1], v[26:27]
	v_pk_mul_f32 v[26:27], v[40:41], v[14:15] op_sel_hi:[1,0]
	v_pk_mul_f32 v[0:1], v[70:71], v[0:1]
	v_pk_mul_f32 v[2:3], v[2:3], v[26:27]
	v_cvt_pk_bf16_f32 v0, v0, v1
	v_pk_mul_f32 v[2:3], v[46:47], v[2:3]
	v_or_b32_e32 v40, s8, v124
	v_cvt_pk_bf16_f32 v1, v2, v3
	global_store_dwordx2 v[24:25], v[0:1], off
	v_mov_b64_e32 v[2:3], v[154:155]
	v_lshl_add_u64 v[0:1], s[8:9], 0, v[208:209]
	v_lshl_add_u64 v[0:1], v[0:1], 2, s[76:77]
	v_mov_b64_e32 v[24:25], v[168:169]
	v_mov_b64_e32 v[26:27], v[170:171]
	v_ashrrev_i32_e32 v41, 31, v40
	v_lshl_add_u64 v[40:41], v[40:41], 1, v[4:5]
	s_mov_b32 s76, s43
	v_lshlrev_b32_e32 v13, 16, v2
	v_and_b32_e32 v15, 0xffff0000, v2
	v_mul_f32_e32 v2, 0xbfb8aa3b, v13
	v_exp_f32_e32 v42, v2
	v_mul_f32_e32 v2, 0xbfb8aa3b, v15
	v_exp_f32_e32 v43, v2
	v_lshlrev_b32_e32 v50, 16, v3
	v_and_b32_e32 v51, 0xffff0000, v3
	v_pk_mul_f32 v[2:3], v[48:49], v[14:15] op_sel_hi:[1,0]
	v_pk_add_f32 v[42:43], v[42:43], 1.0 op_sel_hi:[1,0]
	v_pk_mul_f32 v[2:3], v[24:25], v[2:3]
	v_div_scale_f32 v46, s[4:5], v43, v43, v15
	v_rcp_f32_e32 v47, v46
	s_nop 0
	v_fma_f32 v24, -v46, v47, 1.0
	v_fmac_f32_e32 v47, v24, v47
	v_div_scale_f32 v24, vcc, v15, v43, v15
	v_mul_f32_e32 v25, v24, v47
	v_fma_f32 v48, -v46, v25, v24
	v_fmac_f32_e32 v25, v48, v47
	v_fma_f32 v24, -v46, v25, v24
	v_div_scale_f32 v46, s[4:5], v42, v42, v13
	v_rcp_f32_e32 v48, v46
	v_div_fmas_f32 v24, v24, v47, v25
	v_div_fixup_f32 v25, v24, v43, v15
	v_fma_f32 v15, -v46, v48, 1.0
	v_fmac_f32_e32 v48, v15, v48
	v_div_scale_f32 v15, vcc, v13, v42, v13
	v_mul_f32_e32 v24, v15, v48
	v_fma_f32 v43, -v46, v24, v15
	v_fmac_f32_e32 v24, v43, v48
	v_mul_f32_e32 v43, 0xbfb8aa3b, v50
	v_fma_f32 v15, -v46, v24, v15
	v_exp_f32_e32 v46, v43
	v_mul_f32_e32 v43, 0xbfb8aa3b, v51
	v_exp_f32_e32 v47, v43
	v_div_fmas_f32 v15, v15, v48, v24
	v_div_fixup_f32 v24, v15, v42, v13
	v_pk_mul_f32 v[2:3], v[24:25], v[2:3]
	v_pk_add_f32 v[24:25], v[46:47], 1.0 op_sel_hi:[1,0]
	v_cvt_pk_bf16_f32 v2, v2, v3
	v_div_scale_f32 v13, s[4:5], v25, v25, v51
	v_rcp_f32_e32 v15, v13
	s_nop 0
	v_fma_f32 v3, -v13, v15, 1.0
	v_pk_mul_f32 v[42:43], v[44:45], v[14:15] op_sel_hi:[1,0]
	v_fmac_f32_e32 v15, v3, v15
	v_div_scale_f32 v3, vcc, v51, v25, v51
	v_pk_mul_f32 v[26:27], v[26:27], v[42:43]
	v_mul_f32_e32 v42, v3, v15
	v_fma_f32 v43, -v13, v42, v3
	v_fmac_f32_e32 v42, v43, v15
	v_fma_f32 v3, -v13, v42, v3
	v_div_scale_f32 v13, s[4:5], v24, v24, v50
	v_rcp_f32_e32 v43, v13
	v_div_fmas_f32 v3, v3, v15, v42
	v_div_fixup_f32 v25, v3, v25, v51
	v_fma_f32 v3, -v13, v43, 1.0
	v_fmac_f32_e32 v43, v3, v43
	v_div_scale_f32 v3, vcc, v50, v24, v50
	v_mul_f32_e32 v15, v3, v43
	v_fma_f32 v42, -v13, v15, v3
	v_fmac_f32_e32 v15, v42, v43
	v_fma_f32 v3, -v13, v15, v3
	v_div_fmas_f32 v3, v3, v43, v15
	v_div_fixup_f32 v24, v3, v24, v50
	v_pk_mul_f32 v[24:25], v[24:25], v[26:27]
	v_pk_mul_f32 v[38:39], v[38:39], v[14:15] op_sel_hi:[1,0]
	v_cvt_pk_bf16_f32 v3, v24, v25
	global_store_dwordx2 v[40:41], v[2:3], off
	v_mov_b64_e32 v[2:3], v[156:157]
	s_nop 0
	v_mov_b64_e32 v[24:25], v[172:173]
	v_mov_b64_e32 v[26:27], v[174:175]
	v_or_b32_e32 v40, s8, v123
	v_ashrrev_i32_e32 v41, 31, v40
	v_lshl_add_u64 v[40:41], v[40:41], 1, v[4:5]
	v_lshlrev_b32_e32 v13, 16, v2
	v_and_b32_e32 v15, 0xffff0000, v2
	v_lshlrev_b32_e32 v42, 16, v3
	v_and_b32_e32 v43, 0xffff0000, v3
	v_pk_mul_f32 v[2:3], v[24:25], v[38:39]
	v_mul_f32_e32 v24, 0xbfb8aa3b, v13
	v_mul_f32_e32 v25, 0xbfb8aa3b, v15
	v_exp_f32_e32 v24, v24
	v_exp_f32_e32 v25, v25
	v_mul_f32_e32 v38, 0xbfb8aa3b, v42
	v_mul_f32_e32 v39, 0xbfb8aa3b, v43
	v_exp_f32_e32 v38, v38
	v_pk_add_f32 v[24:25], v[24:25], 1.0 op_sel_hi:[1,0]
	v_exp_f32_e32 v39, v39
	v_div_scale_f32 v44, s[4:5], v25, v25, v15
	v_div_scale_f32 v46, s[4:5], v24, v24, v13
	v_rcp_f32_e32 v47, v44
	v_rcp_f32_e32 v48, v46
	v_div_scale_f32 v45, vcc, v15, v25, v15
	v_fma_f32 v50, -v44, v47, 1.0
	v_fma_f32 v51, -v46, v48, 1.0
	v_fmac_f32_e32 v47, v50, v47
	v_div_scale_f32 v49, s[4:5], v13, v24, v13
	v_fmac_f32_e32 v48, v51, v48
	v_mul_f32_e32 v50, v45, v47
	v_mul_f32_e32 v51, v49, v48
	v_fma_f32 v52, -v44, v50, v45
	v_fma_f32 v53, -v46, v51, v49
	v_fmac_f32_e32 v50, v52, v47
	v_fmac_f32_e32 v51, v53, v48
	v_fma_f32 v44, -v44, v50, v45
	v_fma_f32 v45, -v46, v51, v49
	v_div_fmas_f32 v44, v44, v47, v50
	s_mov_b64 vcc, s[4:5]
	v_div_fixup_f32 v25, v44, v25, v15
	v_div_fmas_f32 v15, v45, v48, v51
	v_div_fixup_f32 v24, v15, v24, v13
	v_pk_mul_f32 v[2:3], v[24:25], v[2:3]
	v_pk_add_f32 v[24:25], v[38:39], 1.0 op_sel_hi:[1,0]
	v_cvt_pk_bf16_f32 v2, v2, v3
	v_div_scale_f32 v13, s[4:5], v25, v25, v43
	v_rcp_f32_e32 v15, v13
	s_nop 0
	v_fma_f32 v3, -v13, v15, 1.0
	v_pk_mul_f32 v[34:35], v[34:35], v[14:15] op_sel_hi:[1,0]
	v_fmac_f32_e32 v15, v3, v15
	v_div_scale_f32 v3, vcc, v43, v25, v43
	v_pk_mul_f32 v[26:27], v[26:27], v[34:35]
	v_mul_f32_e32 v34, v3, v15
	v_fma_f32 v35, -v13, v34, v3
	v_fmac_f32_e32 v34, v35, v15
	v_fma_f32 v3, -v13, v34, v3
	v_div_scale_f32 v13, s[4:5], v24, v24, v42
	v_rcp_f32_e32 v35, v13
	v_div_fmas_f32 v3, v3, v15, v34
	v_div_fixup_f32 v25, v3, v25, v43
	v_fma_f32 v3, -v13, v35, 1.0
	v_fmac_f32_e32 v35, v3, v35
	v_div_scale_f32 v3, vcc, v42, v24, v42
	v_mul_f32_e32 v15, v3, v35
	v_fma_f32 v34, -v13, v15, v3
	v_fmac_f32_e32 v15, v34, v35
	v_fma_f32 v3, -v13, v15, v3
	v_div_fmas_f32 v3, v3, v35, v15
	v_div_fixup_f32 v24, v3, v24, v42
	v_pk_mul_f32 v[24:25], v[24:25], v[26:27]
	v_pk_mul_f32 v[36:37], v[36:37], v[14:15] op_sel_hi:[1,0]
	v_cvt_pk_bf16_f32 v3, v24, v25
	global_store_dwordx2 v[40:41], v[2:3], off
	v_mov_b64_e32 v[2:3], v[158:159]
	s_nop 0
	v_mov_b64_e32 v[24:25], v[176:177]
	v_mov_b64_e32 v[26:27], v[178:179]
	v_pk_mul_f32 v[32:33], v[32:33], v[14:15] op_sel_hi:[1,0]
	v_or_b32_e32 v34, s8, v122
	v_ashrrev_i32_e32 v35, 31, v34
	v_lshl_add_u64 v[34:35], v[34:35], 1, v[4:5]
	v_lshlrev_b32_e32 v13, 16, v2
	v_and_b32_e32 v15, 0xffff0000, v2
	v_lshlrev_b32_e32 v40, 16, v3
	v_and_b32_e32 v41, 0xffff0000, v3
	v_mul_f32_e32 v2, 0xbfb8aa3b, v13
	v_mul_f32_e32 v3, 0xbfb8aa3b, v15
	v_exp_f32_e32 v2, v2
	v_exp_f32_e32 v3, v3
	v_mul_f32_e32 v38, 0xbfb8aa3b, v40
	v_mul_f32_e32 v39, 0xbfb8aa3b, v41
	v_exp_f32_e32 v38, v38
	v_exp_f32_e32 v39, v39
	v_pk_add_f32 v[2:3], v[2:3], 1.0 op_sel_hi:[1,0]
	v_pk_mul_f32 v[24:25], v[24:25], v[36:37]
	v_div_scale_f32 v36, s[4:5], v3, v3, v15
	v_pk_mul_f32 v[26:27], v[26:27], v[32:33]
	v_pk_add_f32 v[32:33], v[38:39], 1.0 op_sel_hi:[1,0]
	v_div_scale_f32 v38, s[4:5], v2, v2, v13
	v_rcp_f32_e32 v45, v36
	v_rcp_f32_e32 v46, v38
	v_div_scale_f32 v42, s[6:7], v33, v33, v41
	v_rcp_f32_e32 v47, v42
	v_fma_f32 v49, -v36, v45, 1.0
	v_div_scale_f32 v37, vcc, v15, v3, v15
	v_fma_f32 v50, -v38, v46, 1.0
	v_fmac_f32_e32 v45, v49, v45
	v_div_scale_f32 v39, s[4:5], v13, v2, v13
	v_fmac_f32_e32 v46, v50, v46
	v_mul_f32_e32 v49, v37, v45
	v_mul_f32_e32 v50, v39, v46
	v_fma_f32 v53, -v36, v49, v37
	v_div_scale_f32 v44, s[8:9], v32, v32, v40
	v_fma_f32 v51, -v42, v47, 1.0
	v_fma_f32 v54, -v38, v50, v39
	v_fmac_f32_e32 v49, v53, v45
	v_div_scale_f32 v43, s[6:7], v41, v33, v41
	v_rcp_f32_e32 v48, v44
	v_fmac_f32_e32 v47, v51, v47
	v_fmac_f32_e32 v50, v54, v46
	v_fma_f32 v36, -v36, v49, v37
	v_mul_f32_e32 v51, v43, v47
	v_fma_f32 v37, -v38, v50, v39
	v_div_fmas_f32 v36, v36, v45, v49
	s_mov_b64 vcc, s[4:5]
	v_fma_f32 v55, -v42, v51, v43
	v_div_fixup_f32 v3, v36, v3, v15
	v_div_fmas_f32 v15, v37, v46, v50
	v_fmac_f32_e32 v51, v55, v47
	v_div_fixup_f32 v2, v15, v2, v13
	v_fma_f32 v52, -v44, v48, 1.0
	v_fma_f32 v38, -v42, v51, v43
	s_mov_b64 vcc, s[6:7]
	v_pk_mul_f32 v[2:3], v[2:3], v[24:25]
	v_div_fmas_f32 v13, v38, v47, v51
	v_cvt_pk_bf16_f32 v2, v2, v3
	v_fmac_f32_e32 v48, v52, v48
	v_div_scale_f32 v3, vcc, v40, v32, v40
	v_div_fixup_f32 v25, v13, v33, v41
	v_mul_f32_e32 v13, v3, v48
	v_fma_f32 v15, -v44, v13, v3
	v_fmac_f32_e32 v13, v15, v48
	v_fma_f32 v3, -v44, v13, v3
	v_div_fmas_f32 v3, v3, v48, v13
	v_div_fixup_f32 v24, v3, v32, v40
	v_pk_mul_f32 v[24:25], v[24:25], v[26:27]
	v_pk_mul_f32 v[28:29], v[28:29], v[14:15] op_sel_hi:[1,0]
	v_cvt_pk_bf16_f32 v3, v24, v25
	global_store_dwordx2 v[34:35], v[2:3], off
	v_mov_b64_e32 v[2:3], v[160:161]
	s_nop 0
	v_mov_b64_e32 v[24:25], v[180:181]
	v_mov_b64_e32 v[26:27], v[182:183]
	v_pk_mul_f32 v[30:31], v[30:31], v[14:15] op_sel_hi:[1,0]
	v_or_b32_e32 v32, 64, v12
	v_ashrrev_i32_e32 v33, 31, v32
	v_lshl_add_u64 v[32:33], v[32:33], 1, v[4:5]
	v_lshlrev_b32_e32 v13, 16, v2
	v_and_b32_e32 v15, 0xffff0000, v2
	v_lshlrev_b32_e32 v36, 16, v3
	v_and_b32_e32 v37, 0xffff0000, v3
	v_mul_f32_e32 v2, 0xbfb8aa3b, v13
	v_mul_f32_e32 v3, 0xbfb8aa3b, v15
	v_exp_f32_e32 v2, v2
	v_exp_f32_e32 v3, v3
	v_mul_f32_e32 v34, 0xbfb8aa3b, v36
	v_mul_f32_e32 v35, 0xbfb8aa3b, v37
	v_exp_f32_e32 v34, v34
	v_exp_f32_e32 v35, v35
	v_pk_add_f32 v[2:3], v[2:3], 1.0 op_sel_hi:[1,0]
	v_pk_mul_f32 v[26:27], v[26:27], v[30:31]
	v_div_scale_f32 v30, s[4:5], v3, v3, v15
	v_pk_mul_f32 v[24:25], v[24:25], v[28:29]
	v_pk_add_f32 v[28:29], v[34:35], 1.0 op_sel_hi:[1,0]
	v_div_scale_f32 v34, s[4:5], v2, v2, v13
	v_rcp_f32_e32 v42, v30
	v_div_scale_f32 v38, s[6:7], v29, v29, v37
	v_rcp_f32_e32 v43, v34
	v_div_scale_f32 v40, s[8:9], v28, v28, v36
	v_rcp_f32_e32 v44, v38
	v_rcp_f32_e32 v45, v40
	v_fma_f32 v46, -v30, v42, 1.0
	v_div_scale_f32 v31, vcc, v15, v3, v15
	v_fma_f32 v47, -v34, v43, 1.0
	v_fmac_f32_e32 v42, v46, v42
	v_div_scale_f32 v35, s[4:5], v13, v2, v13
	v_fma_f32 v48, -v38, v44, 1.0
	v_fmac_f32_e32 v43, v47, v43
	v_mul_f32_e32 v46, v31, v42
	v_div_scale_f32 v39, s[6:7], v37, v29, v37
	v_fma_f32 v49, -v40, v45, 1.0
	v_fmac_f32_e32 v44, v48, v44
	v_mul_f32_e32 v47, v35, v43
	v_fma_f32 v50, -v30, v46, v31
	v_div_scale_f32 v41, s[8:9], v36, v28, v36
	v_fmac_f32_e32 v45, v49, v45
	v_mul_f32_e32 v48, v39, v44
	v_fma_f32 v51, -v34, v47, v35
	v_fmac_f32_e32 v46, v50, v42
	v_mul_f32_e32 v49, v41, v45
	v_fma_f32 v52, -v38, v48, v39
	v_fmac_f32_e32 v47, v51, v43
	v_fma_f32 v30, -v30, v46, v31
	v_fma_f32 v53, -v40, v49, v41
	v_fmac_f32_e32 v48, v52, v44
	v_fma_f32 v31, -v34, v47, v35
	v_div_fmas_f32 v30, v30, v42, v46
	s_mov_b64 vcc, s[4:5]
	v_fmac_f32_e32 v49, v53, v45
	v_fma_f32 v34, -v38, v48, v39
	v_div_fixup_f32 v3, v30, v3, v15
	v_div_fmas_f32 v15, v31, v43, v47
	s_mov_b64 vcc, s[6:7]
	v_fma_f32 v35, -v40, v49, v41
	v_div_fixup_f32 v2, v15, v2, v13
	v_div_fmas_f32 v13, v34, v44, v48
	s_mov_b64 vcc, s[8:9]
	v_pk_mul_f32 v[2:3], v[2:3], v[24:25]
	v_div_fixup_f32 v25, v13, v29, v37
	v_div_fmas_f32 v13, v35, v45, v49
	v_div_fixup_f32 v24, v13, v28, v36
	v_pk_mul_f32 v[24:25], v[24:25], v[26:27]
	v_cvt_pk_bf16_f32 v2, v2, v3
	v_cvt_pk_bf16_f32 v3, v24, v25
	global_store_dwordx2 v[32:33], v[2:3], off
	v_mov_b64_e32 v[2:3], v[162:163]
	s_nop 0
	v_mov_b64_e32 v[24:25], v[184:185]
	v_mov_b64_e32 v[26:27], v[186:187]
	v_pk_mul_f32 v[20:21], v[20:21], v[14:15] op_sel_hi:[1,0]
	v_pk_mul_f32 v[22:23], v[22:23], v[14:15] op_sel_hi:[1,0]
	v_or_b32_e32 v28, 0x50, v12
	v_ashrrev_i32_e32 v29, 31, v28
	v_lshl_add_u64 v[28:29], v[28:29], 1, v[4:5]
	v_lshlrev_b32_e32 v13, 16, v2
	v_and_b32_e32 v15, 0xffff0000, v2
	v_lshlrev_b32_e32 v32, 16, v3
	v_and_b32_e32 v33, 0xffff0000, v3
	v_mul_f32_e32 v2, 0xbfb8aa3b, v13
	v_mul_f32_e32 v3, 0xbfb8aa3b, v15
	v_exp_f32_e32 v2, v2
	v_exp_f32_e32 v3, v3
	v_mul_f32_e32 v30, 0xbfb8aa3b, v32
	v_mul_f32_e32 v31, 0xbfb8aa3b, v33
	v_exp_f32_e32 v30, v30
	v_exp_f32_e32 v31, v31
	v_pk_add_f32 v[2:3], v[2:3], 1.0 op_sel_hi:[1,0]
	v_pk_mul_f32 v[22:23], v[26:27], v[22:23]
	v_div_scale_f32 v26, s[4:5], v3, v3, v15
	v_pk_mul_f32 v[20:21], v[24:25], v[20:21]
	v_pk_add_f32 v[24:25], v[30:31], 1.0 op_sel_hi:[1,0]
	v_div_scale_f32 v30, s[4:5], v2, v2, v13
	v_rcp_f32_e32 v38, v26
	v_div_scale_f32 v34, s[6:7], v25, v25, v33
	v_rcp_f32_e32 v39, v30
	v_div_scale_f32 v36, s[8:9], v24, v24, v32
	v_rcp_f32_e32 v40, v34
	v_rcp_f32_e32 v41, v36
	v_fma_f32 v42, -v26, v38, 1.0
	v_div_scale_f32 v27, vcc, v15, v3, v15
	v_fma_f32 v43, -v30, v39, 1.0
	v_fmac_f32_e32 v38, v42, v38
	v_div_scale_f32 v31, s[4:5], v13, v2, v13
	v_fma_f32 v44, -v34, v40, 1.0
	v_fmac_f32_e32 v39, v43, v39
	v_mul_f32_e32 v42, v27, v38
	v_div_scale_f32 v35, s[6:7], v33, v25, v33
	v_fma_f32 v45, -v36, v41, 1.0
	v_fmac_f32_e32 v40, v44, v40
	v_mul_f32_e32 v43, v31, v39
	v_fma_f32 v46, -v26, v42, v27
	v_div_scale_f32 v37, s[8:9], v32, v24, v32
	v_fmac_f32_e32 v41, v45, v41
	v_mul_f32_e32 v44, v35, v40
	v_fma_f32 v47, -v30, v43, v31
	v_fmac_f32_e32 v42, v46, v38
	v_mul_f32_e32 v45, v37, v41
	v_fma_f32 v48, -v34, v44, v35
	v_fmac_f32_e32 v43, v47, v39
	v_fma_f32 v26, -v26, v42, v27
	v_fma_f32 v49, -v36, v45, v37
	v_fmac_f32_e32 v44, v48, v40
	v_fma_f32 v27, -v30, v43, v31
	v_div_fmas_f32 v26, v26, v38, v42
	s_mov_b64 vcc, s[4:5]
	v_fmac_f32_e32 v45, v49, v41
	v_fma_f32 v30, -v34, v44, v35
	v_div_fixup_f32 v3, v26, v3, v15
	v_div_fmas_f32 v15, v27, v39, v43
	s_mov_b64 vcc, s[6:7]
	v_fma_f32 v31, -v36, v45, v37
	v_div_fixup_f32 v2, v15, v2, v13
	v_div_fmas_f32 v13, v30, v40, v44
	s_mov_b64 vcc, s[8:9]
	v_pk_mul_f32 v[2:3], v[2:3], v[20:21]
	v_div_fixup_f32 v21, v13, v25, v33
	v_div_fmas_f32 v13, v31, v41, v45
	v_div_fixup_f32 v20, v13, v24, v32
	v_pk_mul_f32 v[20:21], v[20:21], v[22:23]
	v_cvt_pk_bf16_f32 v2, v2, v3
	v_cvt_pk_bf16_f32 v3, v20, v21
	global_store_dwordx2 v[28:29], v[2:3], off
	v_mov_b64_e32 v[2:3], v[164:165]
	s_nop 0
	v_mov_b64_e32 v[20:21], v[188:189]
	v_mov_b64_e32 v[22:23], v[190:191]
	v_pk_mul_f32 v[18:19], v[18:19], v[14:15] op_sel_hi:[1,0]
	v_pk_mul_f32 v[16:17], v[16:17], v[14:15] op_sel_hi:[1,0]
	v_or_b32_e32 v24, 0x60, v12
	v_ashrrev_i32_e32 v25, 31, v24
	v_lshl_add_u64 v[24:25], v[24:25], 1, v[4:5]
	v_or_b32_e32 v12, 0x70, v12
	v_lshlrev_b32_e32 v13, 16, v2
	v_and_b32_e32 v15, 0xffff0000, v2
	v_lshlrev_b32_e32 v28, 16, v3
	v_and_b32_e32 v29, 0xffff0000, v3
	v_mul_f32_e32 v2, 0xbfb8aa3b, v13
	v_mul_f32_e32 v3, 0xbfb8aa3b, v15
	v_exp_f32_e32 v2, v2
	v_exp_f32_e32 v3, v3
	v_mul_f32_e32 v26, 0xbfb8aa3b, v28
	v_mul_f32_e32 v27, 0xbfb8aa3b, v29
	v_exp_f32_e32 v26, v26
	v_exp_f32_e32 v27, v27
	v_pk_add_f32 v[2:3], v[2:3], 1.0 op_sel_hi:[1,0]
	v_pk_mul_f32 v[16:17], v[22:23], v[16:17]
	v_div_scale_f32 v22, s[4:5], v3, v3, v15
	v_pk_mul_f32 v[18:19], v[20:21], v[18:19]
	v_pk_add_f32 v[20:21], v[26:27], 1.0 op_sel_hi:[1,0]
	v_div_scale_f32 v26, s[4:5], v2, v2, v13
	v_rcp_f32_e32 v34, v22
	v_div_scale_f32 v30, s[6:7], v21, v21, v29
	v_rcp_f32_e32 v35, v26
	v_div_scale_f32 v32, s[8:9], v20, v20, v28
	v_rcp_f32_e32 v36, v30
	v_rcp_f32_e32 v37, v32
	v_fma_f32 v38, -v22, v34, 1.0
	v_div_scale_f32 v23, vcc, v15, v3, v15
	v_fma_f32 v39, -v26, v35, 1.0
	v_fmac_f32_e32 v34, v38, v34
	v_div_scale_f32 v27, s[4:5], v13, v2, v13
	v_fma_f32 v40, -v30, v36, 1.0
	v_fmac_f32_e32 v35, v39, v35
	v_mul_f32_e32 v38, v23, v34
	v_div_scale_f32 v31, s[6:7], v29, v21, v29
	v_fma_f32 v41, -v32, v37, 1.0
	v_fmac_f32_e32 v36, v40, v36
	v_mul_f32_e32 v39, v27, v35
	v_fma_f32 v42, -v22, v38, v23
	v_div_scale_f32 v33, s[8:9], v28, v20, v28
	v_fmac_f32_e32 v37, v41, v37
	v_mul_f32_e32 v40, v31, v36
	v_fma_f32 v43, -v26, v39, v27
	v_fmac_f32_e32 v38, v42, v34
	v_mul_f32_e32 v41, v33, v37
	v_fma_f32 v44, -v30, v40, v31
	v_fmac_f32_e32 v39, v43, v35
	v_fma_f32 v22, -v22, v38, v23
	v_fma_f32 v45, -v32, v41, v33
	v_fmac_f32_e32 v40, v44, v36
	v_fma_f32 v23, -v26, v39, v27
	v_div_fmas_f32 v22, v22, v34, v38
	s_mov_b64 vcc, s[4:5]
	v_fmac_f32_e32 v41, v45, v37
	v_fma_f32 v26, -v30, v40, v31
	v_div_fixup_f32 v3, v22, v3, v15
	v_div_fmas_f32 v15, v23, v35, v39
	s_mov_b64 vcc, s[6:7]
	v_fma_f32 v27, -v32, v41, v33
	v_div_fixup_f32 v2, v15, v2, v13
	v_div_fmas_f32 v13, v26, v36, v40
	s_mov_b64 vcc, s[8:9]
	v_pk_mul_f32 v[2:3], v[2:3], v[18:19]
	v_div_fixup_f32 v19, v13, v21, v29
	v_div_fmas_f32 v13, v27, v37, v41
	v_div_fixup_f32 v18, v13, v20, v28
	v_pk_mul_f32 v[16:17], v[18:19], v[16:17]
	v_cvt_pk_bf16_f32 v2, v2, v3
	v_cvt_pk_bf16_f32 v3, v16, v17
	global_store_dwordx2 v[24:25], v[2:3], off
	v_mov_b64_e32 v[10:11], v[166:167]
	s_nop 0
	v_mov_b64_e32 v[0:1], v[192:193]
	v_mov_b64_e32 v[2:3], v[194:195]
	v_pk_mul_f32 v[6:7], v[6:7], v[14:15] op_sel_hi:[1,0]
	v_pk_mul_f32 v[8:9], v[8:9], v[14:15] op_sel_hi:[1,0]
	v_ashrrev_i32_e32 v13, 31, v12
	v_lshl_add_u64 v[4:5], v[12:13], 1, v[4:5]
	v_lshlrev_b32_e32 v14, 16, v10
	v_and_b32_e32 v15, 0xffff0000, v10
	v_lshlrev_b32_e32 v16, 16, v11
	v_and_b32_e32 v17, 0xffff0000, v11
	v_mul_f32_e32 v10, 0xbfb8aa3b, v14
	v_mul_f32_e32 v11, 0xbfb8aa3b, v15
	v_exp_f32_e32 v10, v10
	v_exp_f32_e32 v11, v11
	v_mul_f32_e32 v12, 0xbfb8aa3b, v16
	v_mul_f32_e32 v13, 0xbfb8aa3b, v17
	v_exp_f32_e32 v12, v12
	v_exp_f32_e32 v13, v13
	v_pk_mul_f32 v[0:1], v[0:1], v[6:7]
	v_pk_add_f32 v[6:7], v[10:11], 1.0 op_sel_hi:[1,0]
	v_pk_mul_f32 v[2:3], v[2:3], v[8:9]
	v_div_scale_f32 v10, s[4:5], v7, v7, v15
	v_pk_add_f32 v[8:9], v[12:13], 1.0 op_sel_hi:[1,0]
	v_div_scale_f32 v12, s[4:5], v6, v6, v14
	v_rcp_f32_e32 v22, v10
	v_div_scale_f32 v18, s[6:7], v9, v9, v17
	v_rcp_f32_e32 v23, v12
	v_div_scale_f32 v20, s[8:9], v8, v8, v16
	v_rcp_f32_e32 v24, v18
	v_rcp_f32_e32 v25, v20
	v_fma_f32 v26, -v10, v22, 1.0
	v_div_scale_f32 v11, vcc, v15, v7, v15
	v_fma_f32 v27, -v12, v23, 1.0
	v_fmac_f32_e32 v22, v26, v22
	v_div_scale_f32 v13, s[4:5], v14, v6, v14
	v_fma_f32 v28, -v18, v24, 1.0
	v_fmac_f32_e32 v23, v27, v23
	v_mul_f32_e32 v26, v11, v22
	v_div_scale_f32 v19, s[6:7], v17, v9, v17
	v_fma_f32 v29, -v20, v25, 1.0
	v_fmac_f32_e32 v24, v28, v24
	v_mul_f32_e32 v27, v13, v23
	v_fma_f32 v30, -v10, v26, v11
	v_div_scale_f32 v21, s[8:9], v16, v8, v16
	v_fmac_f32_e32 v25, v29, v25
	v_mul_f32_e32 v28, v19, v24
	v_fma_f32 v31, -v12, v27, v13
	v_fmac_f32_e32 v26, v30, v22
	v_mul_f32_e32 v29, v21, v25
	v_fma_f32 v32, -v18, v28, v19
	v_fmac_f32_e32 v27, v31, v23
	v_fma_f32 v10, -v10, v26, v11
	v_fma_f32 v33, -v20, v29, v21
	v_fmac_f32_e32 v28, v32, v24
	v_fma_f32 v11, -v12, v27, v13
	v_div_fmas_f32 v10, v10, v22, v26
	s_mov_b64 vcc, s[4:5]
	v_fmac_f32_e32 v29, v33, v25
	v_fma_f32 v12, -v18, v28, v19
	v_div_fixup_f32 v7, v10, v7, v15
	v_div_fmas_f32 v10, v11, v23, v27
	s_mov_b64 vcc, s[6:7]
	v_fma_f32 v13, -v20, v29, v21
	v_div_fixup_f32 v6, v10, v6, v14
	v_div_fmas_f32 v10, v12, v24, v28
	s_mov_b64 vcc, s[8:9]
	v_pk_mul_f32 v[0:1], v[6:7], v[0:1]
	v_div_fmas_f32 v6, v13, v25, v29
	v_div_fixup_f32 v7, v10, v9, v17
	v_div_fixup_f32 v6, v6, v8, v16
	v_pk_mul_f32 v[2:3], v[6:7], v[2:3]
	v_cvt_pk_bf16_f32 v0, v0, v1
	v_cvt_pk_bf16_f32 v1, v2, v3
	s_mov_b64 s[4:5], 0
	global_store_dwordx2 v[4:5], v[0:1], off

.LBB0_1108:
	s_or_b64 exec, exec, s[4:5]
	v_mov_b32_e32 v0, s48
	s_waitcnt lgkmcnt(0)
	s_barrier
	ds_read_b32 v0, v0
	s_mov_b64 s[4:5], -1
	s_waitcnt lgkmcnt(0)
	v_cmp_lt_i32_e32 vcc, 63, v0
	v_readfirstlane_b32 s6, v0
	s_cbranch_vccnz .LBB0_1101
	s_mov_b64 s[82:83], s[0:1]
	v_mov_b32_e32 v100, v226
	s_load_dwordx2 s[56:57], s[82:83], 0x58
	s_lshl_b32 s5, s6, 1
	s_and_b32 s4, s6, 1
	s_and_b32 s5, s5, -4
	s_sub_i32 s5, 0x7c, s5
	s_or_b32 s6, s4, s38
	s_waitcnt lgkmcnt(0)
	s_add_u32 s80, s56, 0xb400000
	v_readfirstlane_b32 s4, v100
	s_addc_u32 s81, s57, 0
	s_ashr_i32 s7, s4, 8
	s_lshl_b32 s22, s6, 1
	s_bfe_u32 s9, s5, 0x50002
	s_add_i32 s8, s7, s22
	s_lshl_b32 s5, s5, 4
	v_and_b32_e32 v28, 15, v100
	s_or_b32 s5, s5, s39
	s_lshr_b32 s4, s4, 2
	s_lshl_b32 s8, s8, 7
	s_and_b32 s23, s5, 0xfffff800
	s_lshl_b32 s5, s9, 6
	v_and_or_b32 v127, s4, 48, v28
	s_add_i32 s4, s8, 0x800
	s_or_b32 s5, s5, s23
	s_ashr_i32 s4, s4, 7
	v_or_b32_e32 v96, s5, v127
	s_ashr_i32 s5, s4, 31
	s_lshl_b64 s[4:5], s[4:5], 21
	v_ashrrev_i32_e32 v18, 5, v100
	v_ashrrev_i32_e32 v97, 31, v96
	s_add_u32 s4, s80, s4
	v_add_u32_e32 v16, s23, v18
	v_bfe_u32 v29, v100, 4, 2
	s_addc_u32 s5, s81, s5
	v_lshlrev_b64 v[98:99], 8, v[96:97]
	v_ashrrev_i32_e32 v17, 31, v16
	v_lshl_add_u64 v[0:1], s[4:5], 0, v[98:99]
	v_lshlrev_b32_e32 v208, 4, v29
	v_and_b32_e32 v19, 16, v100
	v_lshlrev_b64 v[16:17], 8, v[16:17]
	s_lshl_b32 s4, s6, 22
	v_lshl_add_u64 v[12:13], v[0:1], 0, v[208:209]
	v_lshl_add_u64 v[16:17], s[80:81], 0, v[16:17]
	v_lshl_or_b32 v208, v19, 17, s4
	v_lshlrev_b32_e32 v19, 4, v100
	v_lshl_add_u64 v[16:17], v[16:17], 0, v[208:209]
	v_and_b32_e32 v208, 0xf0, v19
	v_lshl_add_u64 v[16:17], v[16:17], 0, v[208:209]
	v_ashrrev_i32_e32 v19, 3, v100
	s_ashr_i32 s4, s23, 6
	v_lshl_add_u64 v[102:103], v[16:17], 0, s[62:63]
	v_lshl_add_u32 v16, s6, 8, v19
	s_ashr_i32 s5, s4, 31
	v_add_u32_e32 v16, 0x400, v16
	s_lshl_b64 s[4:5], s[4:5], 18
	v_lshlrev_b32_e32 v21, 3, v100
	v_ashrrev_i32_e32 v17, 31, v16
	s_add_u32 s4, s56, s4
	v_and_b32_e32 v22, 56, v21
	s_addc_u32 s5, s57, s5
	v_lshlrev_b64 v[16:17], 7, v[16:17]
	v_lshl_add_u64 v[16:17], s[4:5], 0, v[16:17]
	v_lshlrev_b32_e32 v208, 1, v22
	v_lshl_add_u64 v[16:17], v[16:17], 0, v[208:209]
	v_lshl_add_u64 v[104:105], v[16:17], 0, s[64:65]
	v_mul_lo_u32 v16, v19, s49
	v_add_lshl_u32 v31, v16, v22, 1
	v_lshlrev_b32_e32 v16, 2, v100
	v_sub_u32_e64 v20, s9, 8 clamp
	v_and_b32_e32 v16, 64, v16
	v_add_u32_e32 v16, v16, v18
	v_lshlrev_b32_e32 v208, 18, v20
	v_mul_lo_u32 v56, v16, s28
	v_lshl_add_u64 v[16:17], v[104:105], 0, v[208:209]
	v_add_co_u32_e32 v18, vcc, s21, v16
	v_lshlrev_b32_e32 v208, 14, v20
	v_readfirstlane_b32 s40, v20
	v_and_b32_e32 v57, 0x78, v21
	v_addc_co_u32_e32 v19, vcc, 0, v17, vcc
	v_lshl_add_u64 v[20:21], v[102:103], 0, v[208:209]
	v_add_co_u32_e32 v22, vcc, s35, v20
	global_load_dwordx4 v[0:3], v[12:13], off
	global_load_dwordx4 v[4:7], v[12:13], off offset:64
	global_load_dwordx4 v[8:11], v[12:13], off offset:128
	s_nop 0
	global_load_dwordx4 v[12:15], v[12:13], off offset:192
	v_addc_co_u32_e32 v23, vcc, 0, v21, vcc
	v_add_co_u32_e32 v24, vcc, s20, v16
	s_mul_i32 s4, s7, 0x410
	s_nop 0
	v_addc_co_u32_e32 v25, vcc, 0, v17, vcc
	v_add_co_u32_e32 v26, vcc, s17, v20
	s_add_i32 s41, s4, 0
	s_nop 0
	v_addc_co_u32_e32 v27, vcc, 0, v21, vcc
	global_load_dwordx4 v[52:55], v[24:25], off
	global_load_dwordx4 v[48:51], v[26:27], off
	v_add_co_u32_e32 v24, vcc, s17, v16
	v_lshlrev_b32_e32 v30, 3, v29
	s_nop 0
	v_addc_co_u32_e32 v25, vcc, 0, v17, vcc
	v_add_co_u32_e32 v26, vcc, s34, v20
	s_or_b32 s84, s12, s22
	s_nop 0
	v_addc_co_u32_e32 v27, vcc, 0, v21, vcc
	global_load_dwordx4 v[44:47], v[24:25], off
	global_load_dwordx4 v[40:43], v[26:27], off
	global_load_dwordx4 v[64:67], v[18:19], off
	global_load_dwordx4 v[32:35], v[16:17], off
	global_load_dwordx4 v[60:63], v[22:23], off
	global_load_dwordx4 v[36:39], v[20:21], off
	v_and_b32_e32 v19, 64, v233
	v_xor_b32_e32 v18, 16, v233
	v_add_u32_e32 v19, 64, v19
	v_cmp_lt_i32_e64 s[4:5], v18, v19
	v_max_i32_e32 v20, 2, v100
	v_sub_u32_e32 v20, v20, v100
	v_cndmask_b32_e64 v18, v233, v18, s[4:5]
	v_lshlrev_b32_e32 v126, 2, v18
	v_xor_b32_e32 v18, 32, v233
	v_cmp_lt_i32_e64 s[4:5], v18, v19
	v_add_u32_e32 v20, 0x1ff, v20
	v_lshl_or_b32 v17, s7, 6, v28
	v_cndmask_b32_e64 v18, v233, v18, s[4:5]
	v_lshrrev_b32_e32 v21, 9, v20
	v_mul_lo_u32 v17, v17, s28
	v_lshlrev_b32_e32 v125, 2, v18
	v_lshl_or_b32 v18, s7, 7, v28
	v_add_u32_e32 v21, 1, v21
	v_add_lshl_u32 v16, v56, v57, 1
	v_cmp_lt_i32_e32 vcc, s24, v100
	v_add_lshl_u32 v17, v17, v30, 1
	v_mul_lo_u32 v18, v18, s16
	v_add_u32_e32 v19, 0, v30
	v_lshlrev_b32_e32 v208, 2, v29
	v_and_b32_e32 v129, 0xfffffe, v21
	v_mov_b32_e32 v135, 0
	s_mov_b32 s43, s76
	s_add_i32 s41, s41, 0x23000
	s_mov_b32 s85, s13
	v_not_b32_e32 v128, v208
	v_or_b32_e32 v124, 16, v208
	v_or_b32_e32 v123, 32, v208
	v_or_b32_e32 v122, 48, v208
	v_cmp_lt_u32_e64 s[4:5], s61, v20
	v_lshl_add_u32 v130, v129, 9, v100
	s_mov_b32 s86, s84
	s_mov_b32 s87, s13
	s_mov_b32 s88, s84
	s_mov_b32 s89, s13
	v_add_u32_e32 v101, 0x200, v100
	v_cmp_ne_u32_e64 s[6:7], v21, v129
	v_mov_b32_e32 v136, 0xf149f2ca
	v_add_u32_e32 v131, 0, v16
	v_add_u32_e32 v132, 0, v31
	s_xor_b64 s[90:91], vcc, -1
	v_add_u32_e32 v133, 0, v17
	v_add_u32_e32 v134, v19, v18
	v_and_b32_e32 v149, 15, v100
	v_add_u32_e32 v149, 4, v149
	v_bfe_u32 v149, v149, 3, 1
	v_bfe_u32 v150, v100, 4, 2
	v_xor_b32_e32 v151, v150, v149
	v_lshlrev_b32_e32 v151, 4, v151
	v_lshlrev_b32_e32 v150, 3, v150
	v_sub_u32_e32 v151, v151, v150
	v_add_u32_e32 v134, v134, v151
	v_and_b32_e32 v149, 7, v100
	v_lshlrev_b32_e32 v150, 4, v149
	v_sub_u32_e32 v132, v132, v150
	v_and_b32_e32 v150, 4, v149
	v_lshl_add_u32 v132, v150, 4, v132
	v_and_b32_e32 v150, 1, v149
	v_lshl_add_u32 v132, v150, 5, v132
	v_and_b32_e32 v150, 2, v149
	v_lshl_add_u32 v132, v150, 2, v132
	v_bfe_u32 v150, v100, 3, 4
	v_add_u32_e32 v150, 4, v150
	v_bfe_u32 v150, v150, 3, 1
	v_lshlrev_b32_e32 v150, 4, v150
	v_sub_u32_e32 v148, 16, v150
	v_add_u32_e32 v148, v148, v132
	v_add_u32_e32 v132, v132, v150
	s_mov_b32 s32, 0x11800
	v_bfe_u32 v149, v100, 5, 4
	v_add_u32_e32 v149, 4, v149
	v_bfe_u32 v149, v149, 3, 1
	v_and_b32_e32 v150, 1, v100
	v_lshlrev_b32_e32 v150, 5, v150
	v_sub_u32_e32 v150, 16, v150
	v_mul_i32_i24_e32 v149, v149, v150
	v_add_u32_e32 v131, v131, v149
	v_and_b32_e32 v149, 15, v100
	v_add_u32_e32 v149, 4, v149
	v_bfe_u32 v149, v149, 3, 1
	v_bfe_u32 v150, v100, 4, 1
	v_lshlrev_b32_e32 v150, 5, v150
	v_sub_u32_e32 v150, 16, v150
	v_mul_i32_i24_e32 v149, v149, v150
	v_add_u32_e32 v133, v133, v149
	s_mov_b32 s42, s40
	v_mov_b32_e32 v20, 0
	v_mov_b32_e32 v21, v135
	v_mov_b32_e32 v22, v135
	v_mov_b32_e32 v23, v135
	v_mov_b32_e32 v28, 0
	v_mov_b32_e32 v29, v135
	v_mov_b32_e32 v30, v135
	v_mov_b32_e32 v31, v135
	v_mov_b32_e32 v16, 0
	v_mov_b32_e32 v17, v135
	v_mov_b32_e32 v18, v135
	v_mov_b32_e32 v19, v135
	v_mov_b32_e32 v56, 0
	v_mov_b32_e32 v57, v135
	v_mov_b32_e32 v58, v135
	v_mov_b32_e32 v59, v135
	v_mov_b32_e32 v68, 0
	v_mov_b32_e32 v69, v135
	v_mov_b32_e32 v70, v135
	v_mov_b32_e32 v71, v135
	v_mov_b32_e32 v72, 0
	v_mov_b32_e32 v73, v135
	v_mov_b32_e32 v74, v135
	v_mov_b32_e32 v75, v135
	v_mov_b32_e32 v24, 0
	v_mov_b32_e32 v25, v135
	v_mov_b32_e32 v26, v135
	v_mov_b32_e32 v27, v135
	v_mov_b32_e32 v76, 0
	v_mov_b32_e32 v77, v135
	v_mov_b32_e32 v78, v135
	v_mov_b32_e32 v79, v135
	s_load_dwordx2 s[44:45], s[82:83], 0x40
	v_or_b32_e32 v196, s8, v208
	v_ashrrev_i32_e32 v197, 31, v196
	v_lshlrev_b32_e32 v200, 1, v208
	v_mov_b32_e32 v201, v209
	s_waitcnt lgkmcnt(0)
	s_add_u32 s44, s44, s14
	s_addc_u32 s45, s45, s15
	v_lshl_add_u64 v[196:197], v[196:197], 2, s[44:45]
	s_add_i32 s44, s8, 0x1000
	s_ashr_i32 s44, s44, 7
	s_ashr_i32 s45, s44, 31
	s_lshl_b64 s[44:45], s[44:45], 21
	s_add_u32 s44, s80, s44
	s_addc_u32 s45, s81, s45
	v_lshl_add_u64 v[198:199], s[44:45], 0, v[98:99]
	v_lshl_add_u64 v[198:199], v[198:199], 0, v[200:201]
	global_load_dwordx2 v[202:203], v[198:199], off
	global_load_dwordx2 v[154:155], v[198:199], off offset:32
	global_load_dwordx2 v[156:157], v[198:199], off offset:64
	global_load_dwordx2 v[158:159], v[198:199], off offset:96
	global_load_dwordx2 v[160:161], v[198:199], off offset:128
	global_load_dwordx2 v[162:163], v[198:199], off offset:160
	global_load_dwordx2 v[164:165], v[198:199], off offset:192
	global_load_dwordx2 v[166:167], v[198:199], off offset:224
	global_load_dwordx4 v[168:171], v[196:197], off offset:64
	global_load_dwordx4 v[172:175], v[196:197], off offset:128
	global_load_dwordx4 v[176:179], v[196:197], off offset:192
	global_load_dwordx4 v[180:183], v[196:197], off offset:256
	global_load_dwordx4 v[184:187], v[196:197], off offset:320
	global_load_dwordx4 v[188:191], v[196:197], off offset:384
	global_load_dwordx4 v[192:195], v[196:197], off offset:448
	global_load_dwordx4 v[204:207], v[196:197], off
	s_waitcnt vmcnt(0)
	ds_write_b128 v131, v[36:39]
	ds_write_b64 v132, v[32:33] offset:34816
	ds_write_b64 v148, v[34:35] offset:34816
	ds_write_b128 v131, v[40:43] offset:4352
	ds_write_b64 v132, v[44:45] offset:44032
	ds_write_b64 v148, v[46:47] offset:44032
	ds_write_b128 v131, v[48:51] offset:8704
	ds_write_b64 v132, v[52:53] offset:53248
	ds_write_b64 v148, v[54:55] offset:53248
	ds_write_b128 v131, v[60:63] offset:13056
	ds_write_b64 v132, v[64:65] offset:62464
	ds_write_b64 v148, v[66:67] offset:62464
	s_and_saveexec_b64 s[76:77], s[90:91]
	s_cbranch_execz .Lstg2_bias_done
	s_load_dwordx2 s[92:93], s[82:83], 0x48
	s_mov_b64 s[22:23], -1
	v_mov_b32_e32 v80, v100
	s_and_saveexec_b64 s[94:95], s[4:5]
	s_cbranch_execz .Lstg2_b1115
	s_mov_b64 s[96:97], 0
	v_mov_b32_e32 v82, v129
	v_mov_b64_e32 v[80:81], v[100:101]
.Lstg2_b1113:


	v_mul_hi_i32 v83, v80, s18
	v_lshrrev_b32_e32 v84, 31, v83
	v_ashrrev_i32_e32 v83, 7, v83
	v_add_u32_e32 v84, v83, v84
	v_mul_hi_i32 v83, v81, s18
	v_lshrrev_b32_e32 v85, 31, v83
	v_ashrrev_i32_e32 v83, 7, v83
	v_add_u32_e32 v86, v83, v85
	v_lshl_add_u32 v85, v84, 8, v84
	v_sub_u32_e32 v88, v80, v85
	v_ashrrev_i32_e32 v85, 31, v84
	v_ashrrev_i32_e32 v87, 31, v86
	v_lshl_add_u64 v[94:95], s[86:87], 0, v[84:85]
	s_waitcnt lgkmcnt(0)
	v_mov_b64_e32 v[106:107], s[92:93]
	v_lshl_add_u32 v83, v86, 8, v86
	v_lshl_add_u64 v[92:93], s[88:89], 0, v[86:87]
	v_mad_u64_u32 v[108:109], s[22:23], v94, s19, v[106:107]
	v_sub_u32_e32 v90, v81, v83
	v_ashrrev_i32_e32 v89, 31, v88
	v_mad_i32_i24 v109, v95, s19, v109
	v_mad_u64_u32 v[94:95], s[22:23], v92, s19, v[106:107]
	v_ashrrev_i32_e32 v91, 31, v90
	v_mad_i32_i24 v95, v93, s19, v95
	v_lshl_add_u64 v[92:93], v[88:89], 2, v[108:109]
	v_lshl_add_u64 v[94:95], v[90:91], 2, v[94:95]
	global_load_dword v92, v[92:93], off
	s_nop 0
	global_load_dword v93, v[94:95], off
	v_add_u32_e32 v82, -2, v82
	v_mul_lo_u32 v84, v84, s29
	s_add_i32 s22, 0, 0x23000
	v_lshlrev_b32_e32 v85, 2, v88
	v_cmp_eq_u32_e32 vcc, 0, v82
	v_mul_lo_u32 v83, v86, s29
	v_add3_u32 v84, s22, v84, v85
	v_lshlrev_b32_e32 v85, 2, v90
	v_add_u32_e32 v81, 0x400, v81
	v_add_u32_e32 v80, 0x400, v80
	s_or_b64 s[96:97], vcc, s[96:97]
	v_add3_u32 v83, s22, v83, v85
	s_waitcnt vmcnt(0)
	v_pk_mul_f32 v[92:93], v[92:93], s[60:61] op_sel_hi:[1,0]
	ds_write_b32 v84, v92
	ds_write_b32 v83, v93
	s_andn2_b64 exec, exec, s[96:97]
	s_cbranch_execnz .Lstg2_b1113
	s_or_b64 exec, exec, s[96:97]
	s_orn2_b64 s[22:23], s[6:7], exec
	v_mov_b32_e32 v80, v130

.Lstg2_b1117:


	v_mul_hi_i32 v84, v80, s18
	v_lshrrev_b32_e32 v85, 31, v84
	v_ashrrev_i32_e32 v84, 7, v84
	v_add_u32_e32 v84, v84, v85
	v_ashrrev_i32_e32 v85, 31, v84
	s_waitcnt lgkmcnt(0)
	v_mov_b64_e32 v[82:83], s[92:93]
	v_mul_i32_i24_e32 v90, 0x101, v84
	v_lshl_add_u64 v[88:89], s[84:85], 0, v[84:85]
	v_sub_u32_e32 v86, v80, v90
	v_mad_u64_u32 v[82:83], s[44:45], v88, s19, v[82:83]
	v_ashrrev_i32_e32 v87, 31, v86
	v_mad_i32_i24 v83, v89, s19, v83
	v_lshl_add_u64 v[82:83], v[86:87], 2, v[82:83]
	global_load_dword v82, v[82:83], off
	v_add_u32_e32 v83, 0x200, v80
	v_mul_i32_i24_e32 v84, 0x410, v84
	v_lshlrev_b32_e32 v85, 2, v90
	v_cmp_lt_i32_e32 vcc, 1, v80
	v_mov_b32_e32 v80, v83
	v_sub_u32_e32 v83, v84, v85
	s_or_b64 s[22:23], vcc, s[22:23]
	v_add_u32_e32 v83, v81, v83
	v_add_u32_e32 v81, 0x800, v81
	s_waitcnt vmcnt(0)
	v_mul_f32_e32 v82, 0x3fb8aa3b, v82
	ds_write_b32 v83, v82
	s_andn2_b64 exec, exec, s[22:23]
	s_cbranch_execnz .Lstg2_b1117
.Lstg2_bias_done:
	s_or_b64 exec, exec, s[76:77]
	v_add_u32_e32 v131, s32, v131
	v_add_u32_e32 v132, s32, v132
	v_add_u32_e32 v148, s32, v148
	s_cmp_le_u32 s9, s42
	s_cbranch_scc1 .Lstg2_pro_noload
	s_add_i32 s26, s42, 1
	s_lshl_b32 s22, s26, 6
	s_mov_b32 s23, s27
	s_lshl_b64 s[44:45], s[22:23], 8
	v_lshl_add_u64 v[36:37], v[102:103], 0, s[44:45]
	s_or_b32 s26, s22, 16
	s_lshl_b64 s[44:45], s[26:27], 8
	v_lshl_add_u64 v[40:41], v[102:103], 0, s[44:45]
	s_or_b32 s26, s22, 32
	s_lshl_b64 s[44:45], s[26:27], 8
	v_lshl_add_u64 v[48:49], v[102:103], 0, s[44:45]
	s_or_b32 s26, s22, 48
	s_lshl_b64 s[22:23], s[26:27], 8
	v_lshl_add_u64 v[62:63], v[102:103], 0, s[22:23]
	global_load_dwordx4 v[36:39], v[36:37], off
	global_load_dwordx4 v[40:43], v[40:41], off
	global_load_dwordx4 v[48:51], v[48:49], off
	global_load_dwordx4 v[60:63], v[62:63], off
	s_add_i32 s26, s42, 1
	s_lshl_b64 s[44:45], s[26:27], 18
	v_lshl_add_u64 v[32:33], v[104:105], 0, s[44:45]
	v_add_co_u32_e32 v44, vcc, 0x2000, v32
	s_nop 0
	v_addc_co_u32_e32 v45, vcc, 0, v33, vcc
	v_add_co_u32_e32 v52, vcc, 0x4000, v32
	s_nop 0
	v_addc_co_u32_e32 v53, vcc, 0, v33, vcc
	v_add_co_u32_e32 v64, vcc, 0x6000, v32
	s_nop 0
	v_addc_co_u32_e32 v65, vcc, 0, v33, vcc
	global_load_dwordx4 v[44:47], v[44:45], off
	global_load_dwordx4 v[52:55], v[52:53], off
	global_load_dwordx4 v[64:67], v[64:65], off
	global_load_dwordx4 v[32:35], v[32:33], off
.Lstg2_pro_noload:
.LBB0_1110:
	s_cmp_le_u32 s9, s42
	s_cselect_b64 s[76:77], -1, 0
	s_waitcnt lgkmcnt(0)
	s_barrier

.LBB0_1124:
	s_and_b64 vcc, exec, s[76:77]
	s_cbranch_vccnz .Lstg2_v_done
	s_waitcnt vmcnt(0)
	ds_write_b128 v131, v[36:39]
	ds_write_b64 v132, v[32:33] offset:34816
	ds_write_b64 v148, v[34:35] offset:34816
	ds_write_b128 v131, v[40:43] offset:4352
	ds_write_b64 v132, v[44:45] offset:44032
	ds_write_b64 v148, v[46:47] offset:44032
	ds_write_b128 v131, v[48:51] offset:8704
	ds_write_b64 v132, v[52:53] offset:53248
	ds_write_b64 v148, v[54:55] offset:53248
	ds_write_b128 v131, v[60:63] offset:13056
	ds_write_b64 v132, v[64:65] offset:62464
	ds_write_b64 v148, v[66:67] offset:62464
	s_add_i32 s26, s42, 2
	s_cmp_gt_u32 s26, s9
	s_cbranch_scc1 .Lstg2_v_done
	s_add_i32 s26, s42, 2
	s_lshl_b32 s22, s26, 6
	s_mov_b32 s23, s27
	s_lshl_b64 s[44:45], s[22:23], 8
	v_lshl_add_u64 v[36:37], v[102:103], 0, s[44:45]
	s_or_b32 s26, s22, 16
	s_lshl_b64 s[44:45], s[26:27], 8
	v_lshl_add_u64 v[40:41], v[102:103], 0, s[44:45]
	s_or_b32 s26, s22, 32
	s_lshl_b64 s[44:45], s[26:27], 8
	v_lshl_add_u64 v[48:49], v[102:103], 0, s[44:45]
	s_or_b32 s26, s22, 48
	s_lshl_b64 s[22:23], s[26:27], 8
	v_lshl_add_u64 v[62:63], v[102:103], 0, s[22:23]
	global_load_dwordx4 v[36:39], v[36:37], off
	global_load_dwordx4 v[40:43], v[40:41], off
	global_load_dwordx4 v[48:51], v[48:49], off
	global_load_dwordx4 v[60:63], v[62:63], off
	s_add_i32 s26, s42, 2
	s_lshl_b64 s[44:45], s[26:27], 18
	v_lshl_add_u64 v[32:33], v[104:105], 0, s[44:45]
	v_add_co_u32_e32 v44, vcc, 0x2000, v32
	s_nop 0
	v_addc_co_u32_e32 v45, vcc, 0, v33, vcc
	v_add_co_u32_e32 v52, vcc, 0x4000, v32
	s_nop 0
	v_addc_co_u32_e32 v53, vcc, 0, v33, vcc
	v_add_co_u32_e32 v64, vcc, 0x6000, v32
	s_nop 0
	v_addc_co_u32_e32 v65, vcc, 0, v33, vcc
	global_load_dwordx4 v[44:47], v[44:45], off
	global_load_dwordx4 v[52:55], v[52:53], off
	global_load_dwordx4 v[64:67], v[64:65], off
	global_load_dwordx4 v[32:35], v[32:33], off
.Lstg2_v_done:
	v_max_f32_e32 v81, v137, v137
	v_mov_b32_e32 v80, v81
	s_nop 1
	v_permlane16_swap_b32_e32 v80, v81
	v_max_f32_e32 v80, v80, v81
	v_mov_b32_e32 v81, v80
	s_nop 1
	v_permlane32_swap_b32_e32 v80, v81
	v_max3_f32 v88, v136, v80, v81
	v_sub_f32_e32 v80, v136, v88
	v_exp_f32_e32 v90, v80
	v_sub_f32_e32 v80, v120, v88
	v_exp_f32_e32 v80, v80
	v_sub_f32_e32 v82, v121, v88
	v_exp_f32_e32 v82, v82
	v_sub_f32_e32 v83, v112, v88
	v_exp_f32_e32 v83, v83
	v_sub_f32_e32 v84, v113, v88
	v_exp_f32_e32 v84, v84
	v_sub_f32_e32 v85, v108, v88
	v_fma_f32 v81, v135, v90, v80
	v_exp_f32_e32 v85, v85
	v_sub_f32_e32 v86, v109, v88
	v_add_f32_e32 v81, v82, v81
	v_exp_f32_e32 v86, v86
	v_sub_f32_e32 v87, v106, v88
	v_add_f32_e32 v81, v83, v81
	v_exp_f32_e32 v87, v87
	v_sub_f32_e32 v89, v107, v88
	v_add_f32_e32 v81, v84, v81
	v_exp_f32_e32 v89, v89
	v_add_f32_e32 v81, v85, v81
	v_add_f32_e32 v81, v86, v81
	v_add_f32_e32 v81, v87, v81
	v_add_f32_e32 v91, v89, v81
	v_cvt_pk_bf16_f32 v81, v83, v84
	v_sub_f32_e32 v84, v110, v88
	v_cvt_pk_bf16_f32 v83, v87, v89
	v_exp_f32_e32 v89, v84
	v_sub_f32_e32 v84, v111, v88
	v_exp_f32_e32 v92, v84
	v_sub_f32_e32 v84, v114, v88
	v_exp_f32_e32 v93, v84
	v_sub_f32_e32 v84, v115, v88
	v_exp_f32_e32 v94, v84
	v_sub_f32_e32 v84, v116, v88
	v_exp_f32_e32 v95, v84
	v_sub_f32_e32 v84, v117, v88
	v_exp_f32_e32 v106, v84
	v_sub_f32_e32 v84, v118, v88
	v_exp_f32_e32 v107, v84
	v_sub_f32_e32 v84, v119, v88
	v_exp_f32_e32 v135, v84
	v_cvt_pk_bf16_f32 v84, v89, v92
	v_add_f32_e32 v89, v89, v91
	v_add_f32_e32 v89, v92, v89
	v_add_f32_e32 v89, v93, v89
	v_add_f32_e32 v89, v94, v89
	v_add_f32_e32 v89, v95, v89
	v_cvt_pk_bf16_f32 v80, v80, v82
	v_cvt_pk_bf16_f32 v82, v85, v86
	v_cvt_pk_bf16_f32 v85, v93, v94
	v_add_f32_e32 v89, v106, v89
	v_cvt_pk_bf16_f32 v86, v95, v106
	v_cvt_pk_bf16_f32 v87, v107, v135
	v_pk_mul_f32 v[74:75], v[74:75], v[90:91] op_sel_hi:[1,0]
	v_pk_mul_f32 v[72:73], v[72:73], v[90:91] op_sel_hi:[1,0]
	v_pk_mul_f32 v[70:71], v[70:71], v[90:91] op_sel_hi:[1,0]
	v_pk_mul_f32 v[68:69], v[68:69], v[90:91] op_sel_hi:[1,0]
	v_pk_mul_f32 v[58:59], v[58:59], v[90:91] op_sel_hi:[1,0]
	v_pk_mul_f32 v[56:57], v[56:57], v[90:91] op_sel_hi:[1,0]
	v_pk_mul_f32 v[18:19], v[18:19], v[90:91] op_sel_hi:[1,0]
	v_pk_mul_f32 v[16:17], v[16:17], v[90:91] op_sel_hi:[1,0]
	v_pk_mul_f32 v[30:31], v[30:31], v[90:91] op_sel_hi:[1,0]
	v_pk_mul_f32 v[28:29], v[28:29], v[90:91] op_sel_hi:[1,0]
	v_pk_mul_f32 v[22:23], v[22:23], v[90:91] op_sel_hi:[1,0]
	v_pk_mul_f32 v[20:21], v[20:21], v[90:91] op_sel_hi:[1,0]
	v_pk_mul_f32 v[26:27], v[26:27], v[90:91] op_sel_hi:[1,0]
	v_pk_mul_f32 v[24:25], v[24:25], v[90:91] op_sel_hi:[1,0]
	v_pk_mul_f32 v[78:79], v[78:79], v[90:91] op_sel_hi:[1,0]
	v_pk_mul_f32 v[76:77], v[76:77], v[90:91] op_sel_hi:[1,0]
	v_add_f32_e32 v89, v107, v89
	ds_read_b128 v[90:93], v134 offset:34816
	ds_read_b128 v[106:109], v134 offset:34880
	ds_read_b128 v[110:113], v134 offset:37120
	ds_read_b128 v[114:117], v134 offset:37184
	ds_read_b128 v[118:121], v134 offset:39424
	ds_read_b128 v[136:139], v134 offset:39488
	ds_read_b128 v[140:143], v134 offset:41728
	ds_read_b128 v[144:147], v134 offset:41792
	s_waitcnt lgkmcnt(7)
	v_mfma_f32_16x16x32_bf16 v[72:75], v[90:93], v[80:83], v[72:75]
	s_waitcnt lgkmcnt(5)
	v_mfma_f32_16x16x32_bf16 v[68:71], v[110:113], v[80:83], v[68:71]
	s_waitcnt lgkmcnt(3)
	v_mfma_f32_16x16x32_bf16 v[56:59], v[118:121], v[80:83], v[56:59]
	s_waitcnt lgkmcnt(1)
	v_mfma_f32_16x16x32_bf16 v[16:19], v[140:143], v[80:83], v[16:19]
	v_mfma_f32_16x16x32_bf16 v[72:75], v[106:109], v[84:87], v[72:75]
	v_mfma_f32_16x16x32_bf16 v[68:71], v[114:117], v[84:87], v[68:71]
	v_mfma_f32_16x16x32_bf16 v[56:59], v[136:139], v[84:87], v[56:59]
	s_waitcnt lgkmcnt(0)
	v_mfma_f32_16x16x32_bf16 v[16:19], v[144:147], v[84:87], v[16:19]
	ds_read_b128 v[90:93], v134 offset:44032
	ds_read_b128 v[106:109], v134 offset:44096
	ds_read_b128 v[110:113], v134 offset:46336
	ds_read_b128 v[114:117], v134 offset:46400
	ds_read_b128 v[118:121], v134 offset:48640
	ds_read_b128 v[136:139], v134 offset:48704
	ds_read_b128 v[140:143], v134 offset:50944
	ds_read_b128 v[144:147], v134 offset:51008
	s_waitcnt lgkmcnt(7)
	v_mfma_f32_16x16x32_bf16 v[28:31], v[90:93], v[80:83], v[28:31]
	s_waitcnt lgkmcnt(5)
	v_mfma_f32_16x16x32_bf16 v[20:23], v[110:113], v[80:83], v[20:23]
	s_waitcnt lgkmcnt(3)
	v_mfma_f32_16x16x32_bf16 v[24:27], v[118:121], v[80:83], v[24:27]
	s_waitcnt lgkmcnt(1)
	v_mfma_f32_16x16x32_bf16 v[76:79], v[140:143], v[80:83], v[76:79]
	v_mfma_f32_16x16x32_bf16 v[28:31], v[106:109], v[84:87], v[28:31]
	v_mfma_f32_16x16x32_bf16 v[20:23], v[114:117], v[84:87], v[20:23]
	v_mfma_f32_16x16x32_bf16 v[24:27], v[136:139], v[84:87], v[24:27]
	s_waitcnt lgkmcnt(0)
	v_mfma_f32_16x16x32_bf16 v[76:79], v[144:147], v[84:87], v[76:79]
	v_add_f32_e32 v135, v135, v89
	s_andn2_b64 vcc, exec, s[76:77]
	s_add_i32 s42, s42, 1
	s_cbranch_vccz .LBB0_1100
	v_mov_b32_e32 v136, v88
	v_subrev_u32_e32 v131, s32, v131
	v_subrev_u32_e32 v132, s32, v132
	v_subrev_u32_e32 v148, s32, v148
	v_add_u32_e32 v133, s32, v133
	v_add_u32_e32 v134, s32, v134
	s_sub_i32 s32, 0, s32
	s_branch .LBB0_1110
